# MLA units as 128-query split-key units: the two wave halves alternate over 64-key tiles with separate softmax states merged through LDS at unit end
# baseline (speedup 1.0000x reference)
; DI unsigned pk2(float lo, float hi) { f32x2_t v = {lo, hi}; bf16x2_t b = __builtin_convertvector(v, bf16x2_t); return __builtin_bit_cast(unsigned, b); }
; DI float bflo(unsigned u) { return __uint_as_float(u << 16); }
; DI float bfhi(unsigned u) { return __uint_as_float(u & 0xffff0000u); }
; DI float ex2(float x) { return __builtin_amdgcn_exp2f(x); }
; __global__ void __launch_bounds__(512, 2) mega(Params p) {
;     ...
;                 QUEUE_BEGIN(512 + 256)
;                     if (item >= 256 && item < 512) {
;     ...
;                         const int t0 = (item - 512) * 32;
;                         bf16_t* oc = (bf16_t*)(R1 + R_OA) + (size_t)2 * TC * 512;
;                         const bf16_t* og = (const bf16_t*)(R1 + R_OG);
;                         const float* lse = (const float*)(R1 + R_LSE);
; #pragma unroll
;                         for (int ps = 0; ps < 4; ++ps) {
;                             const int tok = t0 + ps * 8 + (tid >> 6), c8 = (tid & 63) * 8, h = c8 >> 6;
;                             const float l0 = lse[(size_t)tok * 8 + h], l1 = lse[(size_t)(TC + tok) * 8 + h], l2 = lse[(size_t)(2 * TC + tok) * 8 + h];
;                             const float mx = fmaxf(l0, fmaxf(l1, l2));
;                             float w0 = ex2(l0 - mx), w1 = ex2(l1 - mx), w2 = ex2(l2 - mx);
;                             const float is = 1.0f / (w0 + w1 + w2); w0 *= is; w1 *= is; w2 *= is;
;                             const u32x4 a0 = *(const u32x4*)(og + (size_t)tok * 512 + c8), a1 = *(const u32x4*)(og + (size_t)(TC + tok) * 512 + c8), a2 = *(const u32x4*)(og + (size_t)(2 * TC + tok) * 512 + c8);
;                             u32x4 w;
;                             w.x = pk2(w0 * bflo(a0.x) + w1 * bflo(a1.x) + w2 * bflo(a2.x), w0 * bfhi(a0.x) + w1 * bfhi(a1.x) + w2 * bfhi(a2.x));
;                             w.y = pk2(w0 * bflo(a0.y) + w1 * bflo(a1.y) + w2 * bflo(a2.y), w0 * bfhi(a0.y) + w1 * bfhi(a1.y) + w2 * bfhi(a2.y));
;                             w.z = pk2(w0 * bflo(a0.z) + w1 * bflo(a1.z) + w2 * bflo(a2.z), w0 * bfhi(a0.z) + w1 * bfhi(a1.z) + w2 * bfhi(a2.z));
;                             w.w = pk2(w0 * bflo(a0.w) + w1 * bflo(a1.w) + w2 * bflo(a2.w), w0 * bfhi(a0.w) + w1 * bfhi(a1.w) + w2 * bfhi(a2.w));
;                             *(u32x4*)(oc + (size_t)tok * 512 + c8) = w;
;                         }
.LBB0_118:
	s_or_b64 exec, exec, s[6:7]
	s_mov_b32 s0, 0x20000
	s_addk_i32 s0, 0x100
	v_mov_b32_e32 v0, s0
	s_waitcnt lgkmcnt(0)
	s_barrier
	ds_read_b32 v0, v0
	v_readlane_b32 s1, v255, 1
	s_cmp_eq_u32 s1, 0x100
	s_cselect_b32 s1, 0x100, 0
	s_movk_i32 s0, 0x3ff
	s_sub_i32 s0, s0, s1
	s_mov_b64 s[6:7], -1
	s_waitcnt lgkmcnt(0)
	v_cmp_lt_i32_e32 vcc, s0, v0
	v_readfirstlane_b32 s18, v0
	s_cbranch_vccnz .LBB0_113
	s_add_i32 s18, s18, s1
.Lq_have:
	s_cmpk_lt_i32 s18, 0x200
	s_cbranch_scc1 .LBB0_122
	s_addk_i32 s18, 0xff00
	s_and_b32 s0, s18, 0xffffff00
	s_cmpk_lg_i32 s0, 0x100
	s_cbranch_scc0 .LBB0_188
	s_cmpk_gt_i32 s18, 0xff
	s_cbranch_scc0 .LBB0_122
	s_lshl_b32 s0, s18, 5
	v_add_u32_e32 v2, s0, v197
	v_ashrrev_i32_e32 v3, 31, v2
	v_lshlrev_b64 v[4:5], 5, v[2:3]
	v_add_u32_e32 v8, 0x2000, v2
	v_lshl_add_u64 v[4:5], v[136:137], 0, v[4:5]
	v_ashrrev_i32_e32 v9, 31, v8
	global_load_dword v0, v[4:5], off
	v_lshlrev_b64 v[4:5], 5, v[8:9]
	v_add_u32_e32 v12, s0, v196
	v_lshl_add_u64 v[4:5], v[136:137], 0, v[4:5]
	v_ashrrev_i32_e32 v13, 31, v12
	global_load_dword v6, v[4:5], off
	v_lshlrev_b64 v[4:5], 5, v[12:13]
	v_lshl_add_u64 v[4:5], v[136:137], 0, v[4:5]
	global_load_dword v4, v[4:5], off
	v_lshlrev_b64 v[12:13], 10, v[12:13]
	v_lshl_add_u64 v[12:13], v[138:139], 0, v[12:13]
	global_load_dwordx4 v[12:15], v[12:13], off
	v_lshlrev_b64 v[20:21], 10, v[2:3]
	v_lshlrev_b64 v[8:9], 10, v[8:9]
	v_lshl_add_u64 v[8:9], v[138:139], 0, v[8:9]
	s_mov_b64 s[6:7], 0
	s_waitcnt vmcnt(0)
	v_max3_f32 v5, v0, v6, v4
	v_sub_f32_e32 v0, v0, v5
	v_exp_f32_e32 v17, v0
	v_sub_f32_e32 v0, v6, v5
	v_exp_f32_e32 v16, v0
	v_sub_f32_e32 v0, v4, v5
	v_exp_f32_e32 v4, v0
	s_waitcnt vmcnt(0)
	v_lshlrev_b32_e32 v26, 16, v12
	v_add_f32_e32 v0, v17, v16
	v_and_b32_e32 v27, 0xffff0000, v12
	v_add_f32_e32 v0, v4, v0
	v_div_scale_f32 v5, s[0:1], v0, v0, 1.0
	v_rcp_f32_e32 v6, v5
	v_lshlrev_b32_e32 v12, 16, v13
	v_and_b32_e32 v13, 0xffff0000, v13
	v_fma_f32 v7, -v5, v6, 1.0
	v_fmac_f32_e32 v6, v7, v6
	v_div_scale_f32 v7, vcc, 1.0, v0, 1.0
	v_mul_f32_e32 v10, v7, v6
	v_fma_f32 v11, -v5, v10, v7
	v_fmac_f32_e32 v10, v11, v6
	v_fma_f32 v5, -v5, v10, v7
	v_div_fmas_f32 v5, v5, v6, v10
	v_div_fixup_f32 v0, v5, v0, 1.0
	v_mul_f32_e32 v18, v4, v0
	v_lshl_add_u64 v[4:5], v[138:139], 0, v[20:21]
	global_load_dwordx4 v[4:7], v[4:5], off
	v_pk_mul_f32 v[16:17], v[16:17], v[0:1] op_sel_hi:[1,0]
	global_load_dwordx4 v[8:11], v[8:9], off
	s_waitcnt vmcnt(1)
	v_lshlrev_b32_e32 v24, 16, v4
	v_and_b32_e32 v23, 0xffff0000, v4
	s_waitcnt vmcnt(0)
	v_and_b32_e32 v25, 0xffff0000, v8
	v_lshlrev_b32_e32 v22, 16, v8
	v_pk_mul_f32 v[24:25], v[16:17], v[24:25] op_sel:[1,0] op_sel_hi:[0,1]
	v_pk_fma_f32 v[22:23], v[16:17], v[22:23], v[24:25]
	v_lshlrev_b32_e32 v8, 16, v5
	v_pk_fma_f32 v[22:23], v[18:19], v[26:27], v[22:23] op_sel_hi:[0,1,1]
	v_cvt_pk_bf16_f32 v4, v22, v23
	v_lshlrev_b32_e32 v22, 16, v9
	v_and_b32_e32 v9, 0xffff0000, v9
	v_and_b32_e32 v23, 0xffff0000, v5
	v_pk_mul_f32 v[8:9], v[16:17], v[8:9] op_sel:[1,0] op_sel_hi:[0,1]
	v_pk_fma_f32 v[8:9], v[16:17], v[22:23], v[8:9]
	v_lshlrev_b32_e32 v22, 16, v14
	v_pk_fma_f32 v[8:9], v[18:19], v[12:13], v[8:9] op_sel_hi:[0,1,1]
	v_lshlrev_b32_e32 v12, 16, v6
	v_and_b32_e32 v13, 0xffff0000, v10
	v_cvt_pk_bf16_f32 v5, v8, v9
	v_lshlrev_b32_e32 v8, 16, v10
	v_and_b32_e32 v9, 0xffff0000, v6
	v_pk_mul_f32 v[12:13], v[16:17], v[12:13] op_sel:[1,0] op_sel_hi:[0,1]
	v_and_b32_e32 v23, 0xffff0000, v14
	v_pk_fma_f32 v[8:9], v[16:17], v[8:9], v[12:13]
	v_lshlrev_b32_e32 v10, 16, v7
	v_pk_fma_f32 v[8:9], v[18:19], v[22:23], v[8:9] op_sel_hi:[0,1,1]
	v_cvt_pk_bf16_f32 v6, v8, v9
	v_lshlrev_b32_e32 v8, 16, v11
	v_and_b32_e32 v11, 0xffff0000, v11
	v_and_b32_e32 v9, 0xffff0000, v7
	v_pk_mul_f32 v[10:11], v[16:17], v[10:11] op_sel:[1,0] op_sel_hi:[0,1]
	v_pk_fma_f32 v[8:9], v[16:17], v[8:9], v[10:11]
	v_lshlrev_b32_e32 v10, 16, v15
	v_and_b32_e32 v11, 0xffff0000, v15
	v_pk_fma_f32 v[8:9], v[18:19], v[10:11], v[8:9] op_sel_hi:[0,1,1]
	v_cvt_pk_bf16_f32 v7, v8, v9
	v_lshl_add_u64 v[8:9], v[140:141], 0, v[20:21]
	global_store_dwordx4 v[8:9], v[4:7], off
	v_add_u32_e32 v8, 0x2008, v2
	v_ashrrev_i32_e32 v9, 31, v8
	v_add_u32_e32 v4, 8, v2
	v_ashrrev_i32_e32 v5, 31, v4
	v_lshlrev_b64 v[6:7], 5, v[4:5]
	v_lshl_add_u64 v[6:7], v[136:137], 0, v[6:7]
	global_load_dword v0, v[6:7], off
	v_lshlrev_b64 v[6:7], 5, v[8:9]
	v_add_u32_e32 v12, 0x4008, v2
	v_lshl_add_u64 v[6:7], v[136:137], 0, v[6:7]
	v_ashrrev_i32_e32 v13, 31, v12
	global_load_dword v3, v[6:7], off
	v_lshlrev_b64 v[6:7], 5, v[12:13]
	v_lshl_add_u64 v[6:7], v[136:137], 0, v[6:7]
	global_load_dword v6, v[6:7], off
	v_lshlrev_b64 v[20:21], 10, v[4:5]
	v_lshlrev_b64 v[8:9], 10, v[8:9]
	v_lshl_add_u64 v[4:5], v[138:139], 0, v[20:21]
	v_lshl_add_u64 v[8:9], v[138:139], 0, v[8:9]
	v_lshlrev_b64 v[12:13], 10, v[12:13]
	v_lshl_add_u64 v[12:13], v[138:139], 0, v[12:13]
	s_waitcnt vmcnt(0)
	v_max3_f32 v7, v0, v3, v6
	v_sub_f32_e32 v0, v0, v7
	v_exp_f32_e32 v17, v0
	v_sub_f32_e32 v0, v3, v7
	v_exp_f32_e32 v16, v0
	v_sub_f32_e32 v0, v6, v7
	v_exp_f32_e32 v3, v0
	v_add_f32_e32 v0, v17, v16
	v_add_f32_e32 v0, v3, v0
	v_div_scale_f32 v6, s[0:1], v0, v0, 1.0
	v_rcp_f32_e32 v7, v6
	s_nop 0
	v_fma_f32 v10, -v6, v7, 1.0
	v_fmac_f32_e32 v7, v10, v7
	v_div_scale_f32 v10, vcc, 1.0, v0, 1.0
	v_mul_f32_e32 v11, v10, v7
	v_fma_f32 v14, -v6, v11, v10
	v_fmac_f32_e32 v11, v14, v7
	v_fma_f32 v6, -v6, v11, v10
	v_div_fmas_f32 v6, v6, v7, v11
	v_div_fixup_f32 v0, v6, v0, 1.0
	global_load_dwordx4 v[4:7], v[4:5], off
	v_pk_mul_f32 v[16:17], v[16:17], v[0:1] op_sel_hi:[1,0]
	global_load_dwordx4 v[8:11], v[8:9], off
	v_mul_f32_e32 v18, v3, v0
	global_load_dwordx4 v[12:15], v[12:13], off
	s_waitcnt vmcnt(2)
; DI unsigned pk2(float lo, float hi) { f32x2_t v = {lo, hi}; bf16x2_t b = __builtin_convertvector(v, bf16x2_t); return __builtin_bit_cast(unsigned, b); }
; DI float bflo(unsigned u) { return __uint_as_float(u << 16); }
; DI float bfhi(unsigned u) { return __uint_as_float(u & 0xffff0000u); }
; DI float ex2(float x) { return __builtin_amdgcn_exp2f(x); }
; __global__ void __launch_bounds__(512, 2) mega(Params p) {
;     ...
;                         for (int ps = 0; ps < 4; ++ps) {
;                             const int tok = t0 + ps * 8 + (tid >> 6), c8 = (tid & 63) * 8, h = c8 >> 6;
;                             const float l0 = lse[(size_t)tok * 8 + h], l1 = lse[(size_t)(TC + tok) * 8 + h], l2 = lse[(size_t)(2 * TC + tok) * 8 + h];
;                             const float mx = fmaxf(l0, fmaxf(l1, l2));
;                             float w0 = ex2(l0 - mx), w1 = ex2(l1 - mx), w2 = ex2(l2 - mx);
;                             const float is = 1.0f / (w0 + w1 + w2); w0 *= is; w1 *= is; w2 *= is;
;                             const u32x4 a0 = *(const u32x4*)(og + (size_t)tok * 512 + c8), a1 = *(const u32x4*)(og + (size_t)(TC + tok) * 512 + c8), a2 = *(const u32x4*)(og + (size_t)(2 * TC + tok) * 512 + c8);
;                             u32x4 w;
;                             w.x = pk2(w0 * bflo(a0.x) + w1 * bflo(a1.x) + w2 * bflo(a2.x), w0 * bfhi(a0.x) + w1 * bfhi(a1.x) + w2 * bfhi(a2.x));
;                             w.y = pk2(w0 * bflo(a0.y) + w1 * bflo(a1.y) + w2 * bflo(a2.y), w0 * bfhi(a0.y) + w1 * bfhi(a1.y) + w2 * bfhi(a2.y));
;                             w.z = pk2(w0 * bflo(a0.z) + w1 * bflo(a1.z) + w2 * bflo(a2.z), w0 * bfhi(a0.z) + w1 * bfhi(a1.z) + w2 * bfhi(a2.z));
;                             w.w = pk2(w0 * bflo(a0.w) + w1 * bflo(a1.w) + w2 * bflo(a2.w), w0 * bfhi(a0.w) + w1 * bfhi(a1.w) + w2 * bfhi(a2.w));
;                             *(u32x4*)(oc + (size_t)tok * 512 + c8) = w;
;                         }
	v_lshlrev_b32_e32 v24, 16, v4
	v_and_b32_e32 v23, 0xffff0000, v4
	s_waitcnt vmcnt(1)
	v_and_b32_e32 v25, 0xffff0000, v8
	v_lshlrev_b32_e32 v22, 16, v8
	v_pk_mul_f32 v[24:25], v[16:17], v[24:25] op_sel:[1,0] op_sel_hi:[0,1]
	s_waitcnt vmcnt(0)
	v_lshlrev_b32_e32 v26, 16, v12
	v_and_b32_e32 v27, 0xffff0000, v12
	v_pk_fma_f32 v[22:23], v[16:17], v[22:23], v[24:25]
	v_lshlrev_b32_e32 v8, 16, v5
	v_pk_fma_f32 v[22:23], v[18:19], v[26:27], v[22:23] op_sel_hi:[0,1,1]
	v_cvt_pk_bf16_f32 v4, v22, v23
	v_lshlrev_b32_e32 v22, 16, v9
	v_and_b32_e32 v9, 0xffff0000, v9
	v_and_b32_e32 v23, 0xffff0000, v5
	v_pk_mul_f32 v[8:9], v[16:17], v[8:9] op_sel:[1,0] op_sel_hi:[0,1]
	v_lshlrev_b32_e32 v12, 16, v13
	v_and_b32_e32 v13, 0xffff0000, v13
	v_pk_fma_f32 v[8:9], v[16:17], v[22:23], v[8:9]
	v_lshlrev_b32_e32 v22, 16, v14
	v_pk_fma_f32 v[8:9], v[18:19], v[12:13], v[8:9] op_sel_hi:[0,1,1]
	v_lshlrev_b32_e32 v12, 16, v6
	v_and_b32_e32 v13, 0xffff0000, v10
	v_cvt_pk_bf16_f32 v5, v8, v9
	v_lshlrev_b32_e32 v8, 16, v10
	v_and_b32_e32 v9, 0xffff0000, v6
	v_pk_mul_f32 v[12:13], v[16:17], v[12:13] op_sel:[1,0] op_sel_hi:[0,1]
	v_and_b32_e32 v23, 0xffff0000, v14
	v_pk_fma_f32 v[8:9], v[16:17], v[8:9], v[12:13]
	v_lshlrev_b32_e32 v10, 16, v7
	v_pk_fma_f32 v[8:9], v[18:19], v[22:23], v[8:9] op_sel_hi:[0,1,1]
	v_cvt_pk_bf16_f32 v6, v8, v9
	v_lshlrev_b32_e32 v8, 16, v11
	v_and_b32_e32 v11, 0xffff0000, v11
	v_and_b32_e32 v9, 0xffff0000, v7
	v_pk_mul_f32 v[10:11], v[16:17], v[10:11] op_sel:[1,0] op_sel_hi:[0,1]
	v_pk_fma_f32 v[8:9], v[16:17], v[8:9], v[10:11]
	v_lshlrev_b32_e32 v10, 16, v15
	v_and_b32_e32 v11, 0xffff0000, v15
	v_pk_fma_f32 v[8:9], v[18:19], v[10:11], v[8:9] op_sel_hi:[0,1,1]
	v_cvt_pk_bf16_f32 v7, v8, v9
	v_lshl_add_u64 v[8:9], v[140:141], 0, v[20:21]
	global_store_dwordx4 v[8:9], v[4:7], off
	v_add_u32_e32 v8, 0x2010, v2
	v_ashrrev_i32_e32 v9, 31, v8
	v_add_u32_e32 v4, 16, v2
	v_ashrrev_i32_e32 v5, 31, v4
	v_lshlrev_b64 v[6:7], 5, v[4:5]
	v_lshl_add_u64 v[6:7], v[136:137], 0, v[6:7]
	global_load_dword v0, v[6:7], off
	v_lshlrev_b64 v[6:7], 5, v[8:9]
	v_add_u32_e32 v12, 0x4010, v2
	v_lshl_add_u64 v[6:7], v[136:137], 0, v[6:7]
	v_ashrrev_i32_e32 v13, 31, v12
	global_load_dword v3, v[6:7], off
	v_lshlrev_b64 v[6:7], 5, v[12:13]
	v_lshl_add_u64 v[6:7], v[136:137], 0, v[6:7]
	global_load_dword v6, v[6:7], off
	v_lshlrev_b64 v[20:21], 10, v[4:5]
	v_lshlrev_b64 v[8:9], 10, v[8:9]
	v_lshl_add_u64 v[4:5], v[138:139], 0, v[20:21]
	v_lshl_add_u64 v[8:9], v[138:139], 0, v[8:9]
	v_lshlrev_b64 v[12:13], 10, v[12:13]
	v_lshl_add_u64 v[12:13], v[138:139], 0, v[12:13]
	s_waitcnt vmcnt(0)
	v_max3_f32 v7, v0, v3, v6
	v_sub_f32_e32 v0, v0, v7
	v_exp_f32_e32 v17, v0
	v_sub_f32_e32 v0, v3, v7
	v_exp_f32_e32 v16, v0
	v_sub_f32_e32 v0, v6, v7
	v_exp_f32_e32 v3, v0
	v_add_f32_e32 v0, v17, v16
	v_add_f32_e32 v0, v3, v0
	v_div_scale_f32 v6, s[0:1], v0, v0, 1.0
	v_rcp_f32_e32 v7, v6
	s_nop 0
	v_fma_f32 v10, -v6, v7, 1.0
	v_fmac_f32_e32 v7, v10, v7
	v_div_scale_f32 v10, vcc, 1.0, v0, 1.0
	v_mul_f32_e32 v11, v10, v7
	v_fma_f32 v14, -v6, v11, v10
	v_fmac_f32_e32 v11, v14, v7
	v_fma_f32 v6, -v6, v11, v10
	v_div_fmas_f32 v6, v6, v7, v11
	v_div_fixup_f32 v0, v6, v0, 1.0
	global_load_dwordx4 v[4:7], v[4:5], off
	v_pk_mul_f32 v[16:17], v[16:17], v[0:1] op_sel_hi:[1,0]
	global_load_dwordx4 v[8:11], v[8:9], off
	v_mul_f32_e32 v18, v3, v0
	global_load_dwordx4 v[12:15], v[12:13], off
	s_waitcnt vmcnt(2)
	v_lshlrev_b32_e32 v24, 16, v4
	v_and_b32_e32 v23, 0xffff0000, v4
	s_waitcnt vmcnt(1)
	v_and_b32_e32 v25, 0xffff0000, v8
	v_lshlrev_b32_e32 v22, 16, v8
	v_pk_mul_f32 v[24:25], v[16:17], v[24:25] op_sel:[1,0] op_sel_hi:[0,1]
	s_waitcnt vmcnt(0)
	v_lshlrev_b32_e32 v26, 16, v12
	v_and_b32_e32 v27, 0xffff0000, v12
	v_pk_fma_f32 v[22:23], v[16:17], v[22:23], v[24:25]
	v_lshlrev_b32_e32 v8, 16, v5
	v_pk_fma_f32 v[22:23], v[18:19], v[26:27], v[22:23] op_sel_hi:[0,1,1]
	v_cvt_pk_bf16_f32 v4, v22, v23
	v_lshlrev_b32_e32 v22, 16, v9
	v_and_b32_e32 v9, 0xffff0000, v9
	v_and_b32_e32 v23, 0xffff0000, v5
	v_pk_mul_f32 v[8:9], v[16:17], v[8:9] op_sel:[1,0] op_sel_hi:[0,1]
	v_lshlrev_b32_e32 v12, 16, v13
	v_and_b32_e32 v13, 0xffff0000, v13
	v_pk_fma_f32 v[8:9], v[16:17], v[22:23], v[8:9]
	v_lshlrev_b32_e32 v22, 16, v14
	v_pk_fma_f32 v[8:9], v[18:19], v[12:13], v[8:9] op_sel_hi:[0,1,1]
	v_lshlrev_b32_e32 v12, 16, v6
	v_and_b32_e32 v13, 0xffff0000, v10
	v_cvt_pk_bf16_f32 v5, v8, v9
	v_lshlrev_b32_e32 v8, 16, v10
	v_and_b32_e32 v9, 0xffff0000, v6
	v_pk_mul_f32 v[12:13], v[16:17], v[12:13] op_sel:[1,0] op_sel_hi:[0,1]
	v_and_b32_e32 v23, 0xffff0000, v14
	v_pk_fma_f32 v[8:9], v[16:17], v[8:9], v[12:13]
	v_lshlrev_b32_e32 v10, 16, v7
	v_pk_fma_f32 v[8:9], v[18:19], v[22:23], v[8:9] op_sel_hi:[0,1,1]
	v_cvt_pk_bf16_f32 v6, v8, v9
	v_lshlrev_b32_e32 v8, 16, v11
	v_and_b32_e32 v11, 0xffff0000, v11
	v_and_b32_e32 v9, 0xffff0000, v7
	v_pk_mul_f32 v[10:11], v[16:17], v[10:11] op_sel:[1,0] op_sel_hi:[0,1]
	v_pk_fma_f32 v[8:9], v[16:17], v[8:9], v[10:11]
	v_lshlrev_b32_e32 v10, 16, v15
	v_and_b32_e32 v11, 0xffff0000, v15
	v_pk_fma_f32 v[8:9], v[18:19], v[10:11], v[8:9] op_sel_hi:[0,1,1]
	v_cvt_pk_bf16_f32 v7, v8, v9
	v_lshl_add_u64 v[8:9], v[140:141], 0, v[20:21]
	global_store_dwordx4 v[8:9], v[4:7], off
	v_add_u32_e32 v12, 0x4018, v2
	v_ashrrev_i32_e32 v13, 31, v12
	v_add_u32_e32 v4, 24, v2
	v_ashrrev_i32_e32 v5, 31, v4
	v_lshlrev_b64 v[6:7], 5, v[4:5]
	v_add_u32_e32 v8, 0x2018, v2
	v_lshlrev_b64 v[2:3], 5, v[12:13]
	v_lshlrev_b64 v[12:13], 10, v[12:13]
	v_lshl_add_u64 v[6:7], v[136:137], 0, v[6:7]
	v_ashrrev_i32_e32 v9, 31, v8
	v_lshl_add_u64 v[2:3], v[136:137], 0, v[2:3]
	v_lshl_add_u64 v[12:13], v[138:139], 0, v[12:13]
	global_load_dword v0, v[6:7], off
	s_nop 0
	global_load_dwordx4 v[12:15], v[12:13], off
	s_waitcnt vmcnt(0)
; #define LAS __attribute__((address_space(3)))
; template <int MODE>
; DI void attn_unit(LAS unsigned char* lds, const AttnArgs a) {
;     constexpr int DK = ACfg<MODE>::DK, DV = ACfg<MODE>::DV, KLD = DK + 8, VLD = 72, NKS = DK / 16, NDB = DV / 32;
;     const int tid = ltid(), wid = __builtin_amdgcn_readfirstlane(tid >> 6), lane = tid & 63, r32 = lane & 31, hh = lane >> 5;
;     constexpr bool SWZ = (DV == 64);
;     constexpr int BUFE = 64 * KLD + DV * VLD;
;     LAS bf16_t* Ks = (LAS bf16_t*)lds;
;     LAS bf16_t* Vt = Ks + 64 * KLD;
;     LAS float* biasL = (LAS float*)(Ks + 2 * BUFE);
;     const int q0w = a.q0 + wid * 32, qi = q0w + r32;
;     const size_t qtok = (size_t)a.toff + (size_t)qi * a.tstride;
;     bf16x8 qf[NKS];
; #pragma unroll
;     for (int ks = 0; ks < NKS; ++ks) qf[ks] = *(const bf16x8*)(a.Q + qtok * a.ldq + ks * 16 + 8 * hh);
; __global__ void __launch_bounds__(512, 2) mega(Params p) {
;     ...
;                 QUEUE_BEGIN(512 + 256)
;                     if (item >= 256 && item < 512) {
;                         bf16_t* P = (bf16_t*)(R1 + R_P);
;                         const int qt = 15 - ((item - 256) >> 4), bl = (item >> 3) & 1, h = item & 7;
;                         AttnArgs a; a.Q = P + C_SBQ + h * 64; a.ldq = NINP; a.K = P + C_SBK + h * 64; a.ldk = NINP; a.K2 = nullptr; a.ldk2 = 0;
;                         a.V = P + C_SBV + h * 64; a.ldv = NINP; a.O = (bf16_t*)(R1 + R_OA) + h * 64; a.ldo = 512; a.lse = nullptr; a.ldl = 0;
;                         a.q0 = qt * 256; a.tstride = 1; a.toff = bl * SEQ; a.nk = 0; a.c2 = 0.125f * LOG2E; a.biasg = nullptr;
;                         attn_unit<2>(lds, a);
;                     } else if (item < 256) {
;                         const int qt = 15 - (item >> 4), bl = (item >> 3) & 1, h = item & 7;
;                         bf16_t* kvm = (bf16_t*)(R1 + R_KVM);
;                         AttnArgs a; a.Q = (bf16_t*)(R1 + R_QM) + h * 96; a.ldq = 768; a.K = kvm + h * 128; a.ldk = 1024; a.K2 = (bf16_t*)(R1 + R_P) + C_KR; a.ldk2 = NINP;
;                         a.V = kvm + h * 128 + 64; a.ldv = 1024; a.O = (bf16_t*)(R1 + R_OA) + (size_t)TC * 512 + h * 64; a.ldo = 512; a.lse = nullptr; a.ldl = 0;
;                         a.q0 = qt * 256; a.tstride = 1; a.toff = bl * SEQ; a.nk = 0; a.c2 = 0.10206207261596577f * LOG2E; a.biasg = nullptr;
;                         attn_unit<1>(lds, a);
	v_lshlrev_b32_e32 v24, 16, v12
	global_load_dword v2, v[2:3], off
	v_lshlrev_b64 v[6:7], 5, v[8:9]
	v_lshl_add_u64 v[6:7], v[136:137], 0, v[6:7]
	global_load_dword v6, v[6:7], off
	v_lshlrev_b64 v[8:9], 10, v[8:9]
	v_lshl_add_u64 v[8:9], v[138:139], 0, v[8:9]
	v_and_b32_e32 v25, 0xffff0000, v12
	v_lshlrev_b32_e32 v12, 16, v13
	v_and_b32_e32 v13, 0xffff0000, v13
	s_waitcnt vmcnt(0)
	v_max3_f32 v3, v0, v6, v2
	v_sub_f32_e32 v0, v0, v3
	v_exp_f32_e32 v17, v0
	v_sub_f32_e32 v0, v6, v3
	v_exp_f32_e32 v16, v0
	v_sub_f32_e32 v0, v2, v3
	v_exp_f32_e32 v2, v0
	v_add_f32_e32 v0, v17, v16
	v_add_f32_e32 v0, v2, v0
	v_div_scale_f32 v3, s[0:1], v0, v0, 1.0
	v_rcp_f32_e32 v6, v3
	s_nop 0
	v_fma_f32 v7, -v3, v6, 1.0
	v_fmac_f32_e32 v6, v7, v6
	v_div_scale_f32 v7, vcc, 1.0, v0, 1.0
	v_mul_f32_e32 v10, v7, v6
	v_fma_f32 v11, -v3, v10, v7
	v_fmac_f32_e32 v10, v11, v6
	v_fma_f32 v3, -v3, v10, v7
	v_div_fmas_f32 v3, v3, v6, v10
	v_div_fixup_f32 v0, v3, v0, 1.0
	v_lshlrev_b64 v[6:7], 10, v[4:5]
	v_mul_f32_e32 v18, v2, v0
	v_lshl_add_u64 v[2:3], v[138:139], 0, v[6:7]
	global_load_dwordx4 v[2:5], v[2:3], off
	v_pk_mul_f32 v[16:17], v[16:17], v[0:1] op_sel_hi:[1,0]
	global_load_dwordx4 v[8:11], v[8:9], off
	v_lshl_add_u64 v[6:7], v[140:141], 0, v[6:7]
	s_waitcnt vmcnt(1)
	v_lshlrev_b32_e32 v22, 16, v2
	v_and_b32_e32 v21, 0xffff0000, v2
	s_waitcnt vmcnt(0)
	v_and_b32_e32 v23, 0xffff0000, v8
	v_lshlrev_b32_e32 v20, 16, v8
	v_pk_mul_f32 v[22:23], v[16:17], v[22:23] op_sel:[1,0] op_sel_hi:[0,1]
	v_pk_fma_f32 v[20:21], v[16:17], v[20:21], v[22:23]
	v_lshlrev_b32_e32 v8, 16, v3
	v_pk_fma_f32 v[20:21], v[18:19], v[24:25], v[20:21] op_sel_hi:[0,1,1]
	v_cvt_pk_bf16_f32 v2, v20, v21
	v_lshlrev_b32_e32 v20, 16, v9
	v_and_b32_e32 v9, 0xffff0000, v9
	v_and_b32_e32 v21, 0xffff0000, v3
	v_pk_mul_f32 v[8:9], v[16:17], v[8:9] op_sel:[1,0] op_sel_hi:[0,1]
	v_pk_fma_f32 v[8:9], v[16:17], v[20:21], v[8:9]
	v_lshlrev_b32_e32 v20, 16, v14
	v_pk_fma_f32 v[8:9], v[18:19], v[12:13], v[8:9] op_sel_hi:[0,1,1]
	v_lshlrev_b32_e32 v12, 16, v4
	v_and_b32_e32 v13, 0xffff0000, v10
	v_cvt_pk_bf16_f32 v3, v8, v9
	v_lshlrev_b32_e32 v8, 16, v10
	v_and_b32_e32 v9, 0xffff0000, v4
	v_pk_mul_f32 v[12:13], v[16:17], v[12:13] op_sel:[1,0] op_sel_hi:[0,1]
	v_and_b32_e32 v21, 0xffff0000, v14
	v_pk_fma_f32 v[8:9], v[16:17], v[8:9], v[12:13]
	v_lshlrev_b32_e32 v10, 16, v5
	v_pk_fma_f32 v[8:9], v[18:19], v[20:21], v[8:9] op_sel_hi:[0,1,1]
	v_cvt_pk_bf16_f32 v4, v8, v9
	v_lshlrev_b32_e32 v8, 16, v11
	v_and_b32_e32 v11, 0xffff0000, v11
	v_and_b32_e32 v9, 0xffff0000, v5
	v_pk_mul_f32 v[10:11], v[16:17], v[10:11] op_sel:[1,0] op_sel_hi:[0,1]
	v_pk_fma_f32 v[8:9], v[16:17], v[8:9], v[10:11]
	v_lshlrev_b32_e32 v10, 16, v15
	v_and_b32_e32 v11, 0xffff0000, v15
	v_pk_fma_f32 v[8:9], v[18:19], v[10:11], v[8:9] op_sel_hi:[0,1,1]
	v_cvt_pk_bf16_f32 v5, v8, v9
	global_store_dwordx4 v[6:7], v[2:5], off
.LBB0_122:
	s_andn2_b64 vcc, exec, s[6:7]
	s_cbranch_vccnz .LBB0_187
	v_readlane_b32 s100, v255, 13
	v_readlane_b32 s101, v255, 14
	s_and_b32 s1, s18, 7
	s_mul_i32 s0, s1, 0xc0
	v_readlane_b32 s4, v254, 57
	v_readlane_b32 s5, v254, 58
	s_add_u32 s8, s4, s0
	s_addc_u32 s9, s5, 0
	s_lshl_b32 s0, s1, 8
	v_readlane_b32 s4, v254, 55
	v_readlane_b32 s5, v254, 56
	s_add_u32 s6, s4, s0
	s_addc_u32 s7, s5, 0
	s_lshl_b32 s5, s18, 9
	v_mov_b32_e32 v12, v202
	s_lshl_b32 s0, s18, 3
	s_and_b32 s66, s5, 0x1000
	s_and_b32 s0, s0, 0xffffff80
	v_readfirstlane_b32 s5, v12
	s_ashr_i32 s5, s5, 1
	s_sub_i32 s4, 0xf80, s0
	s_lshr_b32 s98, s5, 7
	s_and_b32 s19, s5, 0x60
	v_and_b32_e32 v13, 31, v12
	s_add_i32 s19, s19, s4
	s_waitcnt vmcnt(0)
	v_or_b32_e32 v134, s19, v13
	v_ashrrev_i32_e32 v135, 31, v134
	v_lshl_add_u64 v[132:133], v[134:135], 0, s[66:67]
	v_mov_b64_e32 v[2:3], s[8:9]
	v_bfe_u32 v48, v12, 5, 1
	v_mad_u64_u32 v[2:3], s[8:9], v132, s81, v[2:3]
	v_mad_i32_i24 v3, v133, s81, v3
	v_lshlrev_b32_e32 v0, 4, v48
	v_lshl_add_u64 v[2:3], v[2:3], 0, v[0:1]
	global_load_dwordx4 v[96:99], v[2:3], off
	global_load_dwordx4 v[100:103], v[2:3], off offset:32
	global_load_dwordx4 v[104:107], v[2:3], off offset:64
	global_load_dwordx4 v[108:111], v[2:3], off offset:96
	global_load_dwordx4 v[112:115], v[2:3], off offset:128
	global_load_dwordx4 v[116:119], v[2:3], off offset:160
	s_movk_i32 s5, 0x300
	v_cmp_gt_i32_e64 s[10:11], s5, v12
	s_mov_b32 s5, 0x2aaaaaab
	v_mul_hi_i32 v0, v12, s5
	v_lshrrev_b32_e32 v14, 31, v0
	v_ashrrev_i32_e32 v15, 1, v0
	s_and_saveexec_b64 s[8:9], s[10:11]
	s_cbranch_execz .LBB0_129
	v_add_u32_e32 v2, v15, v14
	v_mul_lo_u32 v0, v2, 12
	v_sub_u32_e32 v0, v12, v0
	v_ashrrev_i32_e32 v3, 31, v2
	v_lshl_add_u64 v[2:3], v[2:3], 0, s[66:67]
	v_cmp_gt_i32_e32 vcc, 8, v0
	v_lshlrev_b32_e32 v0, 3, v0
	s_and_saveexec_b64 s[12:13], vcc
	s_xor_b64 s[12:13], exec, s[12:13]
	v_lshlrev_b64 v[2:3], 11, v[2:3]
	v_lshl_add_u64 v[2:3], s[6:7], 0, v[2:3]
	v_ashrrev_i32_e32 v5, 31, v0
	v_mov_b32_e32 v4, v0
	v_lshl_add_u64 v[4:5], v[4:5], 1, v[2:3]
	s_andn2_saveexec_b64 s[12:13], s[12:13]
	s_cbranch_execz .LBB0_128
	v_readlane_b32 s14, v255, 13
	v_readlane_b32 s15, v255, 14
	s_nop 1
	v_mov_b64_e32 v[4:5], s[14:15]
	v_mad_u64_u32 v[4:5], s[14:15], v2, s86, v[4:5]
	v_mad_i32_i24 v5, v3, s86, v5
	s_movk_i32 s14, 0xff80
	v_lshl_add_u64 v[2:3], v[0:1], 1, v[4:5]
	s_mov_b32 s15, -1
	v_lshl_add_u64 v[4:5], v[2:3], 0, s[14:15]

; template <int MODE>
; DI void attn_unit(LAS unsigned char* lds, const AttnArgs a) {
;     ...
;     if (MODE == 0) ntile = a.nk / 64; else if (MODE == 1) ntile = (a.q0 + 255) / 64 + 1; else if (MODE == 2) ntile = (a.q0 + 254) / 64 + 1; else ntile = 6;
;     ...
;     ATT_LOAD(it0);
;     ATT_STORE(0);
;     __syncthreads();
;     if (it0 + 1 < ntile) ATT_LOAD(it0 + 1);
;     bool sb_dead = false;
.LBB0_153:
	s_mov_b64 s[8:9], -1
	s_cmpk_gt_i32 s4, 0xfec1
	v_lshlrev_b32_e32 v198, 2, v48
	s_cbranch_scc0 .LBB0_184
	v_lshlrev_b32_e32 v142, 2, v48
	v_lshl_add_u64 v[144:145], v[4:5], 1, s[6:7]
	v_lshrrev_b32_e32 v4, 1, v12
	v_and_b32_e32 v5, 12, v4
	v_bitop3_b32 v200, v142, v4, 12 bitop3:0x78
	v_or_b32_e32 v4, 32, v13
	v_or_b32_e32 v3, 8, v142
	v_lshrrev_b32_e32 v4, 1, v4
	v_or_b32_e32 v6, 16, v142
	v_or_b32_e32 v7, 24, v142
	v_or_b32_e32 v8, 32, v142
	v_or_b32_e32 v9, 40, v142
	v_or_b32_e32 v10, 48, v142
	v_or_b32_e32 v11, 56, v142
	v_bitop3_b32 v215, v4, v3, 28 bitop3:0x6c
	v_add_u32_e32 v3, v15, v14
	v_bitop3_b32 v214, v4, v142, 28 bitop3:0x6c
	v_bitop3_b32 v216, v4, v6, 28 bitop3:0x6c
	v_bitop3_b32 v217, v4, v7, 28 bitop3:0x6c
	v_bitop3_b32 v218, v4, v8, 28 bitop3:0x6c
	v_bitop3_b32 v219, v4, v9, 28 bitop3:0x6c
	v_bitop3_b32 v220, v4, v10, 28 bitop3:0x6c
	v_bitop3_b32 v221, v4, v11, 28 bitop3:0x6c
	v_mul_lo_u32 v4, v3, 12
	s_movk_i32 s8, 0x90
	v_sub_u32_e32 v4, v12, v4
	v_add_u32_e32 v6, v52, v51
	v_bitop3_b32 v201, v142, v5, 8 bitop3:0x36
	v_bitop3_b32 v205, v142, v5, 16 bitop3:0x36
	v_bitop3_b32 v208, v142, v5, 24 bitop3:0x36
	v_bitop3_b32 v209, v142, v5, 32 bitop3:0x36
	v_bitop3_b32 v210, v142, v5, 40 bitop3:0x36
	v_bitop3_b32 v211, v142, v5, 48 bitop3:0x36
	v_bitop3_b32 v212, v142, v5, 56 bitop3:0x36
	v_mad_u32_u24 v213, v13, s8, v238
	s_movk_i32 s8, 0xd0
	v_lshlrev_b32_e32 v223, 4, v4
	v_mul_lo_u32 v5, v6, 12
	v_cmp_gt_i32_e64 s[14:15], 8, v4
	v_lshlrev_b32_e32 v4, 3, v4
	v_mul_lo_u32 v222, v3, s8
	v_sub_u32_e32 v7, v50, v5
	v_mul_lo_u32 v224, v6, s8
	v_ashrrev_i32_e32 v5, 31, v4
	v_readlane_b32 s8, v255, 13
	v_lshl_add_u64 v[146:147], v[4:5], 1, s[6:7]
	v_mov_b32_e32 v5, v1
	v_readlane_b32 s9, v255, 14
	s_sub_i32 s0, 0xfff, s0
	s_ashr_i32 s4, s0, 31
	v_lshl_add_u64 v[148:149], v[4:5], 1, s[8:9]
	v_lshlrev_b32_e32 v4, 3, v7
	v_ashrrev_i32_e32 v5, 31, v4
	s_lshr_b32 s4, s4, 26
	v_lshl_add_u64 v[150:151], v[4:5], 1, s[6:7]
	v_mov_b32_e32 v5, v1
	s_add_i32 s0, s0, s4
	v_mul_u32_u24_e32 v0, 0xd0, v13
	v_lshl_add_u64 v[152:153], v[4:5], 1, s[8:9]
	v_lshlrev_b32_e32 v4, 1, v49
	s_movk_i32 s6, 0x100
	v_mov_b32_e32 v14, v1
	v_mov_b32_e32 v15, v1
	s_ashr_i32 s0, s0, 6
	s_lshr_b32 s0, s0, 1
	v_mul_u32_u24_e32 v199, 0x90, v13
	v_lshlrev_b32_e32 v225, 4, v7
	v_cmp_gt_i32_e64 s[16:17], 8, v7
	v_add3_u32 v226, s6, v0, v4
	v_add_u32_e32 v227, 0x80, v3
	v_add_u32_e32 v228, 0x80, v6
	v_add_u32_e32 v229, 0x80, v2
	v_mov_b32_e32 v0, v1
	v_mov_b32_e32 v2, v1
	v_mov_b32_e32 v3, v1
	v_mov_b32_e32 v4, v1
	v_mov_b32_e32 v6, v1
	v_mov_b32_e32 v7, v1
	v_mov_b32_e32 v8, v1
	v_mov_b32_e32 v9, v1
	v_mov_b32_e32 v10, v1
	v_mov_b32_e32 v11, v1
	v_mov_b32_e32 v12, v1
	v_mov_b32_e32 v13, v1
	v_mov_b64_e32 v[30:31], v[14:15]
	v_mov_b64_e32 v[46:47], v[14:15]
	s_or_b32 s4, s19, 31
	s_lshl_b32 s5, s98, 6
	s_max_i32 s20, s0, 0
	v_mov_b32_e32 v135, v134
	v_mov_b32_e32 v230, 0
	v_mov_b32_e32 v232, 0xf149f2ca
	v_mov_b64_e32 v[28:29], v[12:13]
	v_mov_b64_e32 v[26:27], v[10:11]
	v_mov_b64_e32 v[24:25], v[8:9]
	v_mov_b64_e32 v[22:23], v[6:7]
	v_mov_b64_e32 v[20:21], v[4:5]
	v_mov_b64_e32 v[18:19], v[2:3]
	v_mov_b64_e32 v[16:17], v[0:1]
	v_mov_b64_e32 v[44:45], v[12:13]
	v_mov_b64_e32 v[42:43], v[10:11]
	v_mov_b64_e32 v[40:41], v[8:9]
	v_mov_b64_e32 v[38:39], v[6:7]
	v_mov_b64_e32 v[36:37], v[4:5]
	v_mov_b64_e32 v[34:35], v[2:3]
	v_mov_b64_e32 v[32:33], v[0:1]
	v_and_b32_e32 v214, 63, v202
	v_and_b32_e32 v215, 3, v214
	v_bfe_u32 v216, v214, 2, 2
	v_bfe_u32 v217, v214, 4, 1
	v_bfe_u32 v218, v214, 5, 1
	v_lshrrev_b32_e32 v219, 1, v215
	v_lshl_or_b32 v219, v217, 1, v219
	v_and_b32_e32 v220, 2, v216
	v_lshl_or_b32 v219, v220, 1, v219
	v_lshlrev_b32_e32 v219, 4, v219
	v_and_b32_e32 v215, 1, v215
	v_lshl_or_b32 v219, v215, 3, v219
	v_lshl_or_b32 v219, v216, 7, v219
	v_lshl_or_b32 v200, v218, 9, v219
	v_xor_b32_e32 v201, 64, v200
	v_mov_b32_e32 v251, 0x138000
	v_mov_b32_e32 v207, 0x20000
	v_cndmask_b32_e64 v204, v251, v207, s[14:15]
	v_cndmask_b32_e64 v206, v251, v207, s[16:17]
	s_movk_i32 s9, 0x5900
	s_movk_i32 s8, 0x2c00
	s_and_saveexec_b64 s[6:7], s[10:11]
	s_cbranch_execz .Lsk_s1p
	v_add3_u32 v66, s9, v222, v223
	s_waitcnt vmcnt(1)
	ds_write_b128 v66, v[120:123]
.Lsk_s1p:
	s_or_b64 exec, exec, s[6:7]
	s_and_saveexec_b64 s[6:7], s[12:13]
	s_cbranch_execz .Lsk_s2p
	v_add3_u32 v66, s9, v224, v225
	s_waitcnt vmcnt(1)
	ds_write_b128 v66, v[124:127]
.Lsk_s2p:
	s_or_b64 exec, exec, s[6:7]
	v_lshl_add_u32 v66, s8, 1, v143
	s_waitcnt vmcnt(0)
	ds_write_b128 v66, v[128:131] offset:13312
	s_waitcnt lgkmcnt(0)
	s_barrier
	v_sub_u32_e32 v248, v248, v204
	v_sub_u32_e32 v249, v249, v206
	v_subrev_u32_e32 v250, 0x20000, v250
	s_and_saveexec_b64 s[6:7], s[10:11]
	v_lshl_add_u32 v248, v204, 1, v248
	global_load_dwordx4 v[120:123], v248, s[100:101]
	s_or_b64 exec, exec, s[6:7]
	s_and_saveexec_b64 s[6:7], s[12:13]
	s_cbranch_execz .Lsk_l2p
	v_lshl_add_u32 v249, v206, 1, v249
	global_load_dwordx4 v[124:127], v249, s[100:101]
.Lsk_l2p:
	s_or_b64 exec, exec, s[6:7]
	v_add_u32_e32 v250, 0x40000, v250
	global_load_dwordx4 v[128:131], v250, s[100:101] offset:128
	s_and_saveexec_b64 s[6:7], s[10:11]
	v_add_u32_e32 v66, v248, v204
	global_load_dwordx4 v[208:211], v66, s[100:101]
	s_or_b64 exec, exec, s[6:7]
	s_and_saveexec_b64 s[6:7], s[12:13]
	s_cbranch_execz .Lsk_l3p
	v_add_u32_e32 v66, v249, v206
	global_load_dwordx4 v[212:215], v66, s[100:101]
.Lsk_l3p:
	s_or_b64 exec, exec, s[6:7]
	v_add_u32_e32 v66, 0x20000, v250
	global_load_dwordx4 v[216:219], v66, s[100:101] offset:128
	s_mov_b32 s21, 0
	s_and_b32 s8, s21, 1
	s_cmp_gt_i32 s5, s4
	s_cbranch_scc0 .LBB0_156

; #define LAS __attribute__((address_space(3)))
; #define MFMA32(a, b, c) __builtin_amdgcn_mfma_f32_32x32x16_bf16((a), (b), (c), 0, 0, 0)
; template <int MODE>
; DI void attn_unit(LAS unsigned char* lds, const AttnArgs a) {
;     ...
;     for (int it = it0; it < ntile; ++it) {
;         const int kbase = ATT_KBASE(it), cur = (it - it0) & 1;
;         const LAS bf16_t* Kc = Ks + cur * BUFE; const LAS bf16_t* Vc = Vt + cur * BUFE;
;         bool active = true;
;         if (MODE == 1) active = kbase <= q0w + 31;
;         if (MODE == 2) active = (kbase <= q0w + 30) && !sb_dead;
;         if (MODE == 3) active = (kbase + 63 >= q0w - 128) && (kbase <= q0w + 31);
;         if (active) {
;         f32x16 s0, s1;
; #pragma unroll
;         for (int i = 0; i < 16; ++i) { s0[i] = 0.f; s1[i] = 0.f; }
; #pragma unroll
;         for (int ks = 0; ks < NKS; ++ks) {
;             const bf16x8 a0 = *(const LAS bf16x8*)(Kc + r32 * KLD + ks * 16 + 8 * hh);
;             const bf16x8 a1 = *(const LAS bf16x8*)(Kc + (32 + r32) * KLD + ks * 16 + 8 * hh);
;             s0 = MFMA32(a0, qf[ks], s0); s1 = MFMA32(a1, qf[ks], s1);
.LBB0_156:
	s_lshl_b32 s9, s8, 1
	s_add_i32 s9, s9, s98
	s_mul_i32 s9, s9, 0x2c00
	v_lshl_add_u32 v0, s9, 1, v226
	ds_read_b128 v[2:5], v0
	ds_read_b128 v[6:9], v0 offset:6656
	ds_read_b128 v[10:13], v0 offset:32
	ds_read_b128 v[64:67], v0 offset:6688
	ds_read_b128 v[68:71], v0 offset:64
	ds_read_b128 v[72:75], v0 offset:6720
	ds_read_b128 v[76:79], v0 offset:96
	ds_read_b128 v[154:157], v0 offset:6752
	ds_read_b128 v[158:161], v0 offset:128
	ds_read_b128 v[162:165], v0 offset:6784
	ds_read_b128 v[166:169], v0 offset:160
	ds_read_b128 v[170:173], v0 offset:6816
	s_add_i32 s22, s5, 63
	s_mov_b64 s[6:7], -1
	s_cmp_gt_i32 s22, s19
	s_waitcnt lgkmcnt(11)
	v_mfma_f32_32x32x16_bf16 v[48:63], v[2:5], v[96:99], 0
	s_waitcnt lgkmcnt(10)
	v_mfma_f32_32x32x16_bf16 v[80:95], v[6:9], v[96:99], 0
	s_waitcnt lgkmcnt(9)
	v_mfma_f32_32x32x16_bf16 v[48:63], v[10:13], v[100:103], v[48:63]
	s_waitcnt lgkmcnt(8)
	v_mfma_f32_32x32x16_bf16 v[80:95], v[64:67], v[100:103], v[80:95]
	s_waitcnt lgkmcnt(7)
	v_mfma_f32_32x32x16_bf16 v[48:63], v[68:71], v[104:107], v[48:63]
	s_waitcnt lgkmcnt(6)
	v_mfma_f32_32x32x16_bf16 v[80:95], v[72:75], v[104:107], v[80:95]
	s_waitcnt lgkmcnt(5)
	v_mfma_f32_32x32x16_bf16 v[48:63], v[76:79], v[108:111], v[48:63]
	s_waitcnt lgkmcnt(4)
	v_mfma_f32_32x32x16_bf16 v[80:95], v[154:157], v[108:111], v[80:95]
	s_waitcnt lgkmcnt(3)
	v_mfma_f32_32x32x16_bf16 v[48:63], v[158:161], v[112:115], v[48:63]
	s_waitcnt lgkmcnt(2)
	v_mfma_f32_32x32x16_bf16 v[80:95], v[162:165], v[112:115], v[80:95]
	s_waitcnt lgkmcnt(1)
	v_mfma_f32_32x32x16_bf16 v[48:63], v[166:169], v[116:119], v[48:63]
	s_waitcnt lgkmcnt(0)
	v_mfma_f32_32x32x16_bf16 v[80:95], v[170:173], v[116:119], v[80:95]
	s_nop 9
	v_mul_f32_e32 v5, 0x3e16c740, v48
	v_mul_f32_e32 v3, 0x3e16c740, v49
	s_cbranch_scc1 .LBB0_182
	v_max3_f32 v0, v48, v49, v50
	v_max3_f32 v14, v80, v81, v82
	v_max3_f32 v0, v0, v51, v52
	v_max3_f32 v14, v14, v83, v84
	v_max3_f32 v0, v0, v53, v54
	v_max3_f32 v14, v14, v85, v86
	v_max3_f32 v0, v0, v55, v56
	v_max3_f32 v14, v14, v87, v88
	v_max3_f32 v0, v0, v57, v58
	v_max3_f32 v14, v14, v89, v90
	v_max3_f32 v0, v0, v59, v60
	v_max3_f32 v14, v14, v91, v92
	v_max3_f32 v0, v0, v61, v62
	v_max3_f32 v14, v14, v93, v94
	v_max3_f32 v0, v0, v63, v14
	v_and_b32_e32 v4, 64, v243
	v_xor_b32_e32 v5, 32, v243
	v_add_u32_e32 v4, 64, v4
	v_cmp_lt_i32_e32 vcc, v5, v4
	v_max_f32_e32 v0, v0, v95
	v_mul_f32_e32 v0, 0x3e16c740, v0
	v_cndmask_b32_e32 v5, v243, v5, vcc
	v_lshlrev_b32_e32 v5, 2, v5
	ds_bpermute_b32 v3, v5, v0
	s_lshl_b32 s7, s9, 1
	s_mov_b32 s6, 0x3e16c740
	v_add_u32_e32 v158, s7, v200
	v_add_u32_e32 v159, s7, v201
	ds_read_b64_tr_b16 v[64:65], v158 offset:13568
	ds_read_b64_tr_b16 v[66:67], v158 offset:14592
	ds_read_b64_tr_b16 v[68:69], v159 offset:13568
	ds_read_b64_tr_b16 v[70:71], v159 offset:14592
	ds_read_b64_tr_b16 v[72:73], v158 offset:15616
	ds_read_b64_tr_b16 v[74:75], v158 offset:16640
	ds_read_b64_tr_b16 v[76:77], v159 offset:15616
	ds_read_b64_tr_b16 v[78:79], v159 offset:16640
	s_waitcnt lgkmcnt(8)
	v_max3_f32 v231, v232, v0, v3
	v_sub_f32_e32 v2, v232, v231
	v_exp_f32_e32 v2, v2
	v_fma_f32 v48, v48, s6, -v231
	v_fma_f32 v49, v49, s6, -v231
	v_fma_f32 v50, v50, s6, -v231
	v_fma_f32 v51, v51, s6, -v231
	v_fma_f32 v52, v52, s6, -v231
	v_fma_f32 v53, v53, s6, -v231
	v_fma_f32 v54, v54, s6, -v231
	v_fma_f32 v55, v55, s6, -v231
	v_cmp_gt_f32_e32 vcc, 1.0, v2
	s_cbranch_vccz .Lmla_f_nors
	v_pk_mul_f32 v[46:47], v[46:47], v[2:3] op_sel_hi:[1,0]
	v_pk_mul_f32 v[44:45], v[44:45], v[2:3] op_sel_hi:[1,0]
	v_pk_mul_f32 v[42:43], v[42:43], v[2:3] op_sel_hi:[1,0]
	v_pk_mul_f32 v[40:41], v[40:41], v[2:3] op_sel_hi:[1,0]
	v_pk_mul_f32 v[38:39], v[38:39], v[2:3] op_sel_hi:[1,0]
	v_pk_mul_f32 v[36:37], v[36:37], v[2:3] op_sel_hi:[1,0]
	v_pk_mul_f32 v[34:35], v[34:35], v[2:3] op_sel_hi:[1,0]
	v_pk_mul_f32 v[32:33], v[32:33], v[2:3] op_sel_hi:[1,0]
	v_pk_mul_f32 v[30:31], v[30:31], v[2:3] op_sel_hi:[1,0]
	v_pk_mul_f32 v[28:29], v[28:29], v[2:3] op_sel_hi:[1,0]
	v_pk_mul_f32 v[26:27], v[26:27], v[2:3] op_sel_hi:[1,0]
	v_pk_mul_f32 v[24:25], v[24:25], v[2:3] op_sel_hi:[1,0]
	v_pk_mul_f32 v[22:23], v[22:23], v[2:3] op_sel_hi:[1,0]
	v_pk_mul_f32 v[20:21], v[20:21], v[2:3] op_sel_hi:[1,0]
	v_pk_mul_f32 v[18:19], v[18:19], v[2:3] op_sel_hi:[1,0]
	v_pk_mul_f32 v[16:17], v[16:17], v[2:3] op_sel_hi:[1,0]

; #define LAS __attribute__((address_space(3)))
; #define MFMA32(a, b, c) __builtin_amdgcn_mfma_f32_32x32x16_bf16((a), (b), (c), 0, 0, 0)
; #define VFRAG(off) __builtin_shufflevector(*(const LAS s16x4*)(vp + (((off) + 4 * hh) ^ sw)), *(const LAS s16x4*)(vp + (((off) + 8 + 4 * hh) ^ sw)), 0, 1, 2, 3, 4, 5, 6, 7)
; template <int MODE>
; DI void attn_unit(LAS unsigned char* lds, const AttnArgs a) {
;     ...
;         const bf16x8 pb00 = pack8(s0, 0), pb01 = pack8(s0, 1), pb10 = pack8(s1, 0), pb11 = pack8(s1, 1);
; #pragma unroll
;         for (int d = 0; d < NDB; ++d) {
;             const LAS bf16_t* vp = Vc + (d * 32 + r32) * VLD;
;             const int sw = SWZ ? ((((d * 32 + r32) >> 3) & 7) << 2) : 0;
;     ...
;             o[d] = MFMA32(VFRAG(0), pb00, o[d]);
;             o[d] = MFMA32(VFRAG(16), pb01, o[d]);
;             o[d] = MFMA32(VFRAG(32), pb10, o[d]);
;             o[d] = MFMA32(VFRAG(48), pb11, o[d]);
;     ...
;         }
.LBB0_160:
	v_cvt_pk_bf16_f32 v50, v6, v172
	v_cvt_pk_bf16_f32 v6, v233, v0
	v_cvt_pk_bf16_f32 v9, v14, v170
	s_lshl_b32 s7, s9, 1
	v_add_u32_e32 v0, s7, v200
	v_add_u32_e32 v14, s7, v201
	ds_read_b64_tr_b16 v[52:53], v0 offset:13568
	ds_read_b64_tr_b16 v[54:55], v0 offset:14592
	v_fmac_f32_e32 v161, v230, v48
	v_cvt_pk_bf16_f32 v48, v64, v65
	v_cvt_pk_bf16_f32 v49, v4, v166
	v_cvt_pk_bf16_f32 v51, v10, v176
	v_cvt_pk_bf16_f32 v10, v12, v182
	s_waitcnt lgkmcnt(0)
	v_mfma_f32_32x32x16_bf16 v[32:47], v[52:55], v[48:51], v[32:47]
	ds_read_b64_tr_b16 v[52:53], v0 offset:15616
	ds_read_b64_tr_b16 v[54:55], v0 offset:16640
	v_cvt_pk_bf16_f32 v11, v158, v188
	v_cvt_pk_bf16_f32 v12, v168, v192
	v_cvt_pk_bf16_f32 v13, v184, v194
	v_cvt_pk_bf16_f32 v7, v2, v160
	s_waitcnt lgkmcnt(0)
	v_mfma_f32_32x32x16_bf16 v[32:47], v[52:55], v[10:13], v[32:47]
	ds_read_b64_tr_b16 v[52:53], v0 offset:17664
	ds_read_b64_tr_b16 v[54:55], v0 offset:18688
	v_cvt_pk_bf16_f32 v8, v8, v164
	v_cvt_pk_bf16_f32 v2, v154, v174
	s_waitcnt lgkmcnt(0)
	v_mfma_f32_32x32x16_bf16 v[32:47], v[52:55], v[6:9], v[32:47]
	ds_read_b64_tr_b16 v[52:53], v0 offset:19712
	ds_read_b64_tr_b16 v[54:55], v0 offset:20736
	v_cvt_pk_bf16_f32 v3, v156, v180
	v_cvt_pk_bf16_f32 v4, v162, v186
	v_cvt_pk_bf16_f32 v5, v178, v190
	v_mov_b32_e32 v230, v161
	s_waitcnt lgkmcnt(0)
	v_mfma_f32_32x32x16_bf16 v[32:47], v[52:55], v[2:5], v[32:47]
	ds_read_b64_tr_b16 v[52:53], v14 offset:13568
	ds_read_b64_tr_b16 v[54:55], v14 offset:14592
	s_waitcnt lgkmcnt(0)
	v_mfma_f32_32x32x16_bf16 v[16:31], v[52:55], v[48:51], v[16:31]
	ds_read_b64_tr_b16 v[48:49], v14 offset:15616
	ds_read_b64_tr_b16 v[50:51], v14 offset:16640
	s_waitcnt lgkmcnt(0)
	v_mfma_f32_32x32x16_bf16 v[16:31], v[48:51], v[10:13], v[16:31]
	ds_read_b64_tr_b16 v[10:11], v14 offset:17664
	ds_read_b64_tr_b16 v[12:13], v14 offset:18688
	s_waitcnt lgkmcnt(0)
	v_mfma_f32_32x32x16_bf16 v[16:31], v[10:13], v[6:9], v[16:31]
	ds_read_b64_tr_b16 v[6:7], v14 offset:19712
	ds_read_b64_tr_b16 v[8:9], v14 offset:20736
	s_waitcnt lgkmcnt(0)
	v_mfma_f32_32x32x16_bf16 v[16:31], v[6:9], v[2:5], v[16:31]

; template <int MODE>
; DI void attn_unit(LAS unsigned char* lds, const AttnArgs a) {
;     ...
;         if (it + 1 < ntile) ATT_STORE(cur ^ 1);
;         if (MODE == 2) {
;             sb_dead = (__ballot(carry != 0.f) == 0ull);
;             if (!__syncthreads_or(sb_dead ? 0 : 1)) break;
;         } else __syncthreads();
;         if (it + 2 < ntile) ATT_LOAD(it + 2);
.LBB0_161:
	s_xor_b32 s8, s8, 1
	s_mulk_i32 s8, 0x5800
	s_lshl_b32 s6, s8, 1
	s_add_i32 s9, s6, 0x100
	s_and_saveexec_b64 s[6:7], s[10:11]
	s_cbranch_execz .Lsk_s1a
	v_add3_u32 v66, s9, v222, v223
	s_waitcnt vmcnt(3)
	ds_write_b128 v66, v[120:123]
.Lsk_s1a:
	s_or_b64 exec, exec, s[6:7]
	s_and_saveexec_b64 s[6:7], s[12:13]
	s_cbranch_execz .Lsk_s2a
	v_add3_u32 v66, s9, v224, v225
	s_waitcnt vmcnt(3)
	ds_write_b128 v66, v[124:127]
.Lsk_s2a:
	s_or_b64 exec, exec, s[6:7]
	v_lshl_add_u32 v66, s8, 1, v143
	s_waitcnt vmcnt(2)
	ds_write_b128 v66, v[128:131] offset:13312
	s_and_saveexec_b64 s[6:7], s[10:11]
	s_cbranch_execz .Lsk_s1b
	v_add3_u32 v66, s9, v222, v223
	s_waitcnt vmcnt(1)
	ds_write_b128 v66, v[208:211] offset:22528
.Lsk_s1b:
	s_or_b64 exec, exec, s[6:7]
	s_and_saveexec_b64 s[6:7], s[12:13]
	s_cbranch_execz .Lsk_s2b
	v_add3_u32 v66, s9, v224, v225
	s_waitcnt vmcnt(1)
	ds_write_b128 v66, v[212:215] offset:22528
.Lsk_s2b:
	s_or_b64 exec, exec, s[6:7]
	v_lshl_add_u32 v66, s8, 1, v143
	s_waitcnt vmcnt(0)
	ds_write_b128 v66, v[216:219] offset:35840
.LBB0_166:
	s_add_i32 s6, s21, 2
	s_cmp_gt_i32 s6, s0
	s_waitcnt lgkmcnt(0)
	s_barrier
	s_cbranch_scc1 .LBB0_180
	s_and_saveexec_b64 s[6:7], s[10:11]
	v_lshl_add_u32 v248, v204, 1, v248
	global_load_dwordx4 v[120:123], v248, s[100:101]
	s_or_b64 exec, exec, s[6:7]
	s_and_saveexec_b64 s[6:7], s[12:13]
	s_cbranch_execz .Lsk_l2l
	v_lshl_add_u32 v249, v206, 1, v249
	global_load_dwordx4 v[124:127], v249, s[100:101]

; template <int MODE>
; DI void attn_unit(LAS unsigned char* lds, const AttnArgs a) {
;     ...
;     for (int it = it0; it < ntile; ++it) {
;     ...
;         if (it + 2 < ntile) ATT_LOAD(it + 2);
;     }
.Lsk_l3l:
	s_or_b64 exec, exec, s[6:7]
	v_add_u32_e32 v66, 0x20000, v250
	global_load_dwordx4 v[216:219], v66, s[100:101] offset:128
.LBB0_180:
	s_add_i32 s5, s5, 0x80
	s_add_i32 s6, s21, 1
	s_cmp_lg_u32 s21, s20
	s_cbranch_scc0 .LBB0_222
	v_mov_b32_e32 v232, v231
	s_mov_b32 s21, s6
	s_and_b32 s8, s21, 1
	s_cmp_gt_i32 s5, s4
	s_cbranch_scc1 .LBB0_155
	s_branch .LBB0_156

; DI unsigned pk2(float lo, float hi) { f32x2_t v = {lo, hi}; bf16x2_t b = __builtin_convertvector(v, bf16x2_t); return __builtin_bit_cast(unsigned, b); }
; DI float lg2(float x) { return __builtin_amdgcn_logf(x); }
; template <int MODE>
; DI void attn_unit(LAS unsigned char* lds, const AttnArgs a) {
;     ...
;     float inv = 1.f;
;     if (MODE != 2) {
;         const float lt = lrow + __shfl_xor(lrow, 32);
;         inv = 1.0f / lt;
;         if (MODE == 3 && hh == 0) a.lse[qtok * a.ldl] = mrow + lg2(lt);
;     }
; #pragma unroll
;     for (int d = 0; d < NDB; ++d)
; #pragma unroll
;         for (int g4 = 0; g4 < 4; ++g4) {
;             u32x2 w; w.x = pk2(o[d][4 * g4] * inv, o[d][4 * g4 + 1] * inv); w.y = pk2(o[d][4 * g4 + 2] * inv, o[d][4 * g4 + 3] * inv);
;             *(u32x2*)(a.O + qtok * a.ldo + d * 32 + 8 * g4 + 4 * hh) = w;
;         }
.LBB0_222:
	v_and_b32_e32 v66, 0xff, v202
	v_lshlrev_b32_e32 v66, 2, v66
	v_add_u32_e32 v66, 0x100, v66
	s_cmp_eq_u32 s98, 0
	s_cbranch_scc1 .Lsk_m1
	ds_write_b32 v66, v231
	ds_write_b32 v66, v230 offset:1024
	ds_write_b32 v66, v16 offset:2048
	ds_write_b32 v66, v17 offset:3072
	ds_write_b32 v66, v18 offset:4096
	ds_write_b32 v66, v19 offset:5120
	ds_write_b32 v66, v20 offset:6144
	ds_write_b32 v66, v21 offset:7168
	ds_write_b32 v66, v22 offset:8192
	ds_write_b32 v66, v23 offset:9216
	ds_write_b32 v66, v24 offset:10240
	ds_write_b32 v66, v25 offset:11264
	ds_write_b32 v66, v26 offset:12288
	ds_write_b32 v66, v27 offset:13312
	ds_write_b32 v66, v28 offset:14336
	ds_write_b32 v66, v29 offset:15360
	ds_write_b32 v66, v30 offset:16384
	ds_write_b32 v66, v31 offset:17408
	ds_write_b32 v66, v32 offset:18432
	ds_write_b32 v66, v33 offset:19456
	ds_write_b32 v66, v34 offset:20480
	ds_write_b32 v66, v35 offset:21504
	ds_write_b32 v66, v36 offset:22528
	ds_write_b32 v66, v37 offset:23552
	ds_write_b32 v66, v38 offset:24576
	ds_write_b32 v66, v39 offset:25600
	ds_write_b32 v66, v40 offset:26624
	ds_write_b32 v66, v41 offset:27648
	ds_write_b32 v66, v42 offset:28672
	ds_write_b32 v66, v43 offset:29696
	ds_write_b32 v66, v44 offset:30720
	ds_write_b32 v66, v45 offset:31744
	ds_write_b32 v66, v46 offset:32768
	ds_write_b32 v66, v47 offset:33792
.Lsk_m1:
	s_waitcnt lgkmcnt(0)
	s_barrier
	s_cmp_lg_u32 s98, 0
	s_cbranch_scc1 .LBB0_187
	ds_read_b32 v67, v66
	ds_read_b32 v68, v66 offset:1024
	ds_read_b32 v154, v66 offset:2048
	ds_read_b32 v155, v66 offset:3072
	ds_read_b32 v156, v66 offset:4096
	ds_read_b32 v157, v66 offset:5120
	ds_read_b32 v158, v66 offset:6144
	ds_read_b32 v159, v66 offset:7168
	ds_read_b32 v160, v66 offset:8192
	ds_read_b32 v161, v66 offset:9216
	ds_read_b32 v162, v66 offset:10240
	ds_read_b32 v163, v66 offset:11264
	ds_read_b32 v164, v66 offset:12288
	ds_read_b32 v165, v66 offset:13312
	ds_read_b32 v166, v66 offset:14336
	ds_read_b32 v167, v66 offset:15360
	ds_read_b32 v168, v66 offset:16384
	ds_read_b32 v169, v66 offset:17408
	ds_read_b32 v170, v66 offset:18432
	ds_read_b32 v171, v66 offset:19456
	ds_read_b32 v172, v66 offset:20480
	ds_read_b32 v173, v66 offset:21504
	ds_read_b32 v174, v66 offset:22528
	ds_read_b32 v175, v66 offset:23552
	ds_read_b32 v176, v66 offset:24576
	ds_read_b32 v177, v66 offset:25600
	ds_read_b32 v178, v66 offset:26624
	ds_read_b32 v179, v66 offset:27648
	ds_read_b32 v180, v66 offset:28672
	ds_read_b32 v181, v66 offset:29696
	ds_read_b32 v182, v66 offset:30720
	ds_read_b32 v183, v66 offset:31744
	ds_read_b32 v184, v66 offset:32768
	ds_read_b32 v185, v66 offset:33792
	s_waitcnt lgkmcnt(0)
	v_max_f32_e32 v69, v231, v67
	v_sub_f32_e32 v70, v231, v69
	v_sub_f32_e32 v71, v67, v69
	v_exp_f32_e32 v70, v70
	v_exp_f32_e32 v71, v71
	s_nop 0
	v_mul_f32_e32 v230, v230, v70
	v_fmac_f32_e32 v230, v68, v71
	v_mul_f32_e32 v16, v16, v70
	v_fmac_f32_e32 v16, v154, v71
	v_mul_f32_e32 v17, v17, v70
	v_fmac_f32_e32 v17, v155, v71
	v_mul_f32_e32 v18, v18, v70
	v_fmac_f32_e32 v18, v156, v71
	v_mul_f32_e32 v19, v19, v70
	v_fmac_f32_e32 v19, v157, v71
	v_mul_f32_e32 v20, v20, v70
	v_fmac_f32_e32 v20, v158, v71
	v_mul_f32_e32 v21, v21, v70
	v_fmac_f32_e32 v21, v159, v71
	v_mul_f32_e32 v22, v22, v70
	v_fmac_f32_e32 v22, v160, v71
	v_mul_f32_e32 v23, v23, v70
	v_fmac_f32_e32 v23, v161, v71
	v_mul_f32_e32 v24, v24, v70
	v_fmac_f32_e32 v24, v162, v71
	v_mul_f32_e32 v25, v25, v70
	v_fmac_f32_e32 v25, v163, v71
	v_mul_f32_e32 v26, v26, v70
	v_fmac_f32_e32 v26, v164, v71
	v_mul_f32_e32 v27, v27, v70
	v_fmac_f32_e32 v27, v165, v71
	v_mul_f32_e32 v28, v28, v70
	v_fmac_f32_e32 v28, v166, v71
	v_mul_f32_e32 v29, v29, v70
	v_fmac_f32_e32 v29, v167, v71
	v_mul_f32_e32 v30, v30, v70
	v_fmac_f32_e32 v30, v168, v71
	v_mul_f32_e32 v31, v31, v70
	v_fmac_f32_e32 v31, v169, v71
	v_mul_f32_e32 v32, v32, v70
	v_fmac_f32_e32 v32, v170, v71
	v_mul_f32_e32 v33, v33, v70
	v_fmac_f32_e32 v33, v171, v71
	v_mul_f32_e32 v34, v34, v70
	v_fmac_f32_e32 v34, v172, v71
	v_mul_f32_e32 v35, v35, v70
	v_fmac_f32_e32 v35, v173, v71
	v_mul_f32_e32 v36, v36, v70
	v_fmac_f32_e32 v36, v174, v71
	v_mul_f32_e32 v37, v37, v70
	v_fmac_f32_e32 v37, v175, v71
	v_mul_f32_e32 v38, v38, v70
	v_fmac_f32_e32 v38, v176, v71
	v_mul_f32_e32 v39, v39, v70
	v_fmac_f32_e32 v39, v177, v71
	v_mul_f32_e32 v40, v40, v70
	v_fmac_f32_e32 v40, v178, v71
	v_mul_f32_e32 v41, v41, v70
	v_fmac_f32_e32 v41, v179, v71
	v_mul_f32_e32 v42, v42, v70
	v_fmac_f32_e32 v42, v180, v71
	v_mul_f32_e32 v43, v43, v70
	v_fmac_f32_e32 v43, v181, v71
	v_mul_f32_e32 v44, v44, v70
	v_fmac_f32_e32 v44, v182, v71
	v_mul_f32_e32 v45, v45, v70
	v_fmac_f32_e32 v45, v183, v71
	v_mul_f32_e32 v46, v46, v70
	v_fmac_f32_e32 v46, v184, v71
	v_mul_f32_e32 v47, v47, v70
	v_fmac_f32_e32 v47, v185, v71
	s_branch .LBB0_186
